# nt (streaming) hint on the select_row score loads (read once)
# baseline (speedup 1.0000x reference)
; DI size_t sc_rowoff(int b, int t) { const int c = t >> 6; return (size_t)b * SC_PB + (size_t)4096 * (c * (c + 1) / 2) + (size_t)(t & 63) * (64 * (c + 1)); }
; DI void select_row(const float* SC, unsigned* dmask, int b, int t, int lane) {
;     unsigned* dm = dmask + ((size_t)b * SEQ + t) * 64;
;     const int nvalid = t + 1;
;     if (nvalid <= 256) {
;         const int w = lane;
;         const int lo = 32 * w; unsigned bits = 0u;
;         if (lo + 31 <= t) bits = 0xffffffffu; else if (lo <= t) bits = (2u << (t - lo)) - 1u;
;         dm[w] = bits; return;
;     }
;     const int nch = (nvalid + 255) >> 8;
;     const float* srow = SC + sc_rowoff(b, t) + 4 * lane;
;     unsigned u[8][4];
; #pragma unroll
;     for (int k = 0; k < 8; ++k) {
;         if (k < nch) {
;             const f32x4 v = *(const f32x4*)(srow + 256 * k);
; #pragma unroll
;             for (int e = 0; e < 4; ++e) { const unsigned bits = __builtin_bit_cast(unsigned, v[e] + 0.0f); const unsigned key = ((int)bits < 0) ? ~bits : (bits | 0x80000000u);
;                 u[k][e] = (256 * k + 4 * lane + e <= t) ? key : 0u; }
;         } else { u[k][0] = 0u; u[k][1] = 0u; u[k][2] = 0u; u[k][3] = 0u; }
;     }
.LBB0_535:
	s_and_b64 vcc, exec, s[76:77]
	s_cbranch_vccnz .LBB0_476
	s_mul_i32 s11, s64, s20
	s_add_i32 s11, s11, s92
	s_and_b32 s10, s11, 15
	s_ashr_i32 s65, s11, 4
	s_lshl_b32 s8, s10, 11
	s_ashr_i32 s9, s65, 31
	s_add_u32 s8, s8, s65
	s_addc_u32 s9, 0, s9
	s_lshl_b64 s[8:9], s[8:9], 8
	s_add_u32 s48, s21, s8
	s_addc_u32 s49, s68, s9
	s_cmpk_gt_i32 s65, 0xff
	s_mov_b64 s[8:9], -1
	s_cbranch_scc0 .LBB0_657
	s_lshr_b32 s8, s65, 6
	s_add_i32 s9, s8, 1
	s_mul_i32 s8, s9, s8
	s_lshr_b32 s14, s8, 1
	s_bfe_u32 s8, s11, 0x60004
	s_lshl_b32 s11, s9, 6
	s_mul_hi_u32 s9, s11, s8
	s_mul_i32 s8, s11, s8
	s_lshl_b64 s[8:9], s[8:9], 2
	s_add_u32 s8, s44, s8
	s_addc_u32 s9, s45, s9
	s_mul_i32 s10, s10, 0x840000
	s_add_u32 s10, s8, s10
	s_addc_u32 s11, s9, 0
	s_lshl_b64 s[8:9], s[14:15], 14
	s_add_u32 s8, s10, s8
	s_addc_u32 s9, s11, s9
	global_load_dwordx4 v[6:9], v120, s[8:9] nt
	global_load_dwordx4 v[2:5], v120, s[8:9] offset:1024 nt
	s_add_u32 s98, s8, 0x1000
	s_addc_u32 s99, s9, 0
	s_cmpk_lt_u32 s65, 0x200
	s_cbranch_scc1 .Lsel_pf_done
	global_load_dwordx4 v[150:153], v120, s[8:9] offset:2048 nt
	s_cmpk_lt_u32 s65, 0x300
	s_cbranch_scc1 .Lsel_pf_done
	global_load_dwordx4 v[154:157], v120, s[8:9] offset:3072 nt
	s_cmpk_lt_u32 s65, 0x400
	s_cbranch_scc1 .Lsel_pf_done
	global_load_dwordx4 v[158:161], v120, s[98:99] nt
	s_cmpk_lt_u32 s65, 0x500
	s_cbranch_scc1 .Lsel_pf_done
	global_load_dwordx4 v[162:165], v120, s[98:99] offset:1024 nt
	s_cmpk_lt_u32 s65, 0x600
	s_cbranch_scc1 .Lsel_pf_done
	global_load_dwordx4 v[166:169], v120, s[98:99] offset:2048 nt
	s_cmpk_lt_u32 s65, 0x700
	s_cbranch_scc1 .Lsel_pf_done
	global_load_dwordx4 v[170:173], v120, s[98:99] offset:3072 nt
